# bundle11 + P8/P11 epilogue: second-round residual loads issued up front into free VGPRs (hides one memory round trip per unit)
# baseline (speedup 1.0000x reference)
.LBB0_1411:
	s_lshl_b32 s37, s44, 8
	s_add_i32 s37, s37, s59
	v_or_b32_e32 v166, s37, v180
	v_lshl_or_b32 v164, s65, 8, v182
	v_ashrrev_i32_e32 v167, 31, v166
	v_ashrrev_i32_e32 v165, 31, v164
	v_lshlrev_b64 v[130:131], 11, v[166:167]
	v_lshl_add_u64 v[130:131], v[130:131], 0, v[164:165]
	v_lshlrev_b64 v[204:205], 1, v[130:131]
	v_lshl_add_u64 v[130:131], s[12:13], 0, v[204:205]
	v_or_b32_e32 v206, 0x100, v204
	v_mov_b32_e32 v207, v205
	global_load_dwordx4 v[188:191], v[130:131], off
	v_lshl_add_u64 v[130:131], s[12:13], 0, v[206:207]
	global_load_dwordx4 v[192:195], v[130:131], off
	v_or_b32_e32 v130, 16, v166
	v_or_b32_e32 v132, 32, v166
	v_or_b32_e32 v134, 48, v166
	v_ashrrev_i32_e32 v131, 31, v130
	v_ashrrev_i32_e32 v133, 31, v132
	v_ashrrev_i32_e32 v135, 31, v134
	v_lshlrev_b64 v[130:131], 11, v[130:131]
	v_lshlrev_b64 v[132:133], 11, v[132:133]
	v_lshlrev_b64 v[134:135], 11, v[134:135]
	v_lshl_add_u64 v[130:131], v[130:131], 0, v[164:165]
	v_lshl_add_u64 v[132:133], v[132:133], 0, v[164:165]
	v_lshl_add_u64 v[134:135], v[134:135], 0, v[164:165]
	v_lshlrev_b64 v[178:179], 1, v[130:131]
	v_lshlrev_b64 v[174:175], 1, v[132:133]
	v_lshlrev_b64 v[168:169], 1, v[134:135]
	v_or_b32_e32 v176, 0x100, v178
	v_mov_b32_e32 v177, v179
	v_or_b32_e32 v172, 0x100, v174
	v_mov_b32_e32 v173, v175
	v_lshl_add_u64 v[130:131], s[12:13], 0, v[178:179]
	v_lshl_add_u64 v[132:133], s[12:13], 0, v[174:175]
	v_lshl_add_u64 v[134:135], s[12:13], 0, v[168:169]
	v_or_b32_e32 v170, 0x100, v168
	v_mov_b32_e32 v171, v169
	v_lshl_add_u64 v[136:137], s[12:13], 0, v[176:177]
	v_lshl_add_u64 v[138:139], s[12:13], 0, v[172:173]
	v_lshl_add_u64 v[208:209], s[12:13], 0, v[170:171]
	global_load_dwordx4 v[196:199], v[130:131], off
	global_load_dwordx4 v[200:203], v[136:137], off
	global_load_dwordx4 v[142:145], v[132:133], off
	s_nop 0
	global_load_dwordx4 v[138:141], v[138:139], off
	s_nop 0
	global_load_dwordx4 v[134:137], v[134:135], off
	s_nop 0
	global_load_dwordx4 v[130:133], v[208:209], off
	s_add_u32 s98, s12, 0x80000
	s_addc_u32 s99, s13, 0
	global_load_dwordx4 v[220:223], v204, s[98:99]
	global_load_dwordx4 v[224:227], v206, s[98:99]
	global_load_dwordx4 v[228:231], v178, s[98:99]
	global_load_dwordx4 v[232:235], v176, s[98:99]
	global_load_dwordx4 v[236:239], v174, s[98:99]
	global_load_dwordx4 v[240:243], v172, s[98:99]
	global_load_dwordx4 v[244:247], v168, s[98:99]
	global_load_dwordx4 v[248:251], v170, s[98:99]
	v_or_b32_e32 v162, s37, v252
	s_waitcnt vmcnt(8)
	v_lshlrev_b32_e32 v208, 16, v188
	v_and_b32_e32 v209, 0xffff0000, v188
	v_lshlrev_b32_e32 v188, 16, v189
	v_and_b32_e32 v189, 0xffff0000, v189
	v_lshlrev_b32_e32 v210, 16, v190
	v_and_b32_e32 v211, 0xffff0000, v190
	v_lshlrev_b32_e32 v190, 16, v191
	v_and_b32_e32 v191, 0xffff0000, v191
	v_pk_add_f32 v[126:127], v[126:127], v[208:209]
	v_lshlrev_b32_e32 v208, 16, v192
	v_and_b32_e32 v209, 0xffff0000, v192
	v_lshlrev_b32_e32 v192, 16, v193
	v_and_b32_e32 v193, 0xffff0000, v193
	v_pk_add_f32 v[128:129], v[128:129], v[188:189]
	v_pk_add_f32 v[188:189], v[124:125], v[190:191]
	v_pk_add_f32 v[190:191], v[122:123], v[210:211]
	v_lshlrev_b32_e32 v210, 16, v194
	v_and_b32_e32 v211, 0xffff0000, v194
	v_lshlrev_b32_e32 v194, 16, v195
	v_and_b32_e32 v195, 0xffff0000, v195
	v_pk_add_f32 v[120:121], v[120:121], v[192:193]
	v_pk_add_f32 v[118:119], v[118:119], v[208:209]
	v_pk_add_f32 v[192:193], v[116:117], v[194:195]
	v_pk_add_f32 v[194:195], v[114:115], v[210:211]
	v_mul_f32_e32 v114, v119, v119
	v_mul_f32_e32 v115, v120, v120
	v_fmac_f32_e32 v114, v118, v118
	v_fmac_f32_e32 v115, v121, v121
	v_cvt_pk_bf16_f32 v122, v126, v127
	v_cvt_pk_bf16_f32 v123, v128, v129
	v_mul_f32_e32 v1, v127, v127
	v_mul_f32_e32 v127, v128, v128
	v_mul_f32_e32 v128, v190, v190
	v_mul_f32_e32 v163, v188, v188
	v_mul_f32_e32 v116, v194, v194
	v_add_f32_e32 v114, v114, v115
	v_mul_f32_e32 v115, v192, v192
	v_fmac_f32_e32 v1, v126, v126
	v_fmac_f32_e32 v127, v129, v129
	v_fmac_f32_e32 v128, v191, v191
	v_fmac_f32_e32 v163, v189, v189
	v_fmac_f32_e32 v116, v195, v195
	v_fmac_f32_e32 v115, v193, v193
	v_add_f32_e32 v1, v1, v127
	v_add_f32_e32 v117, v163, v128
	v_add_f32_e32 v115, v115, v116
	v_add_f32_e32 v1, v117, v1
	v_add_f32_e32 v114, v115, v114
	v_and_b32_e32 v115, 64, v186
	v_add_f32_e32 v1, v1, v114
	v_xor_b32_e32 v114, 16, v186
	v_add_u32_e32 v115, 64, v115
	v_cmp_lt_i32_e32 vcc, v114, v115
	v_lshl_add_u64 v[116:117], s[14:15], 0, v[204:205]
	v_cvt_pk_bf16_f32 v124, v190, v191
	v_cvt_pk_bf16_f32 v125, v188, v189
	global_store_dwordx4 v[116:117], v[122:125], off
	v_cndmask_b32_e32 v114, v186, v114, vcc
	v_lshlrev_b32_e32 v114, 2, v114
	ds_bpermute_b32 v126, v114, v1
	v_cvt_pk_bf16_f32 v116, v118, v119
	v_xor_b32_e32 v118, 32, v186
	v_cmp_lt_i32_e32 vcc, v118, v115
	v_cvt_pk_bf16_f32 v117, v120, v121
	s_waitcnt lgkmcnt(0)
	v_add_f32_e32 v1, v1, v126
	v_lshl_add_u64 v[120:121], s[14:15], 0, v[206:207]
	v_cndmask_b32_e32 v115, v186, v118, vcc
	v_lshlrev_b32_e32 v115, 2, v115
	ds_bpermute_b32 v122, v115, v1
	v_cvt_pk_bf16_f32 v118, v194, v195
	v_cvt_pk_bf16_f32 v119, v192, v193
	global_store_dwordx4 v[120:121], v[116:119], off
	v_lshlrev_b32_e32 v120, 16, v198
	v_and_b32_e32 v121, 0xffff0000, v198
	v_lshlrev_b32_e32 v116, 16, v196
	v_and_b32_e32 v117, 0xffff0000, v196
	v_lshlrev_b32_e32 v118, 16, v197
	v_and_b32_e32 v119, 0xffff0000, v197
	v_pk_add_f32 v[110:111], v[110:111], v[116:117]
	v_pk_add_f32 v[112:113], v[112:113], v[118:119]
	v_pk_add_f32 v[118:119], v[106:107], v[120:121]
	v_cvt_pk_bf16_f32 v106, v110, v111
	v_mul_f32_e32 v111, v111, v111
	s_waitcnt lgkmcnt(0)
	v_add_f32_e32 v1, v1, v122
	v_lshlrev_b32_e32 v122, 16, v199
	v_and_b32_e32 v123, 0xffff0000, v199
	v_fmac_f32_e32 v111, v110, v110
	v_mul_f32_e32 v110, v112, v112
	v_pk_add_f32 v[116:117], v[108:109], v[122:123]
	v_fmac_f32_e32 v110, v113, v113
	v_cvt_pk_bf16_f32 v107, v112, v113
	v_add_f32_e32 v110, v111, v110
	v_mul_f32_e32 v111, v118, v118
	v_mul_f32_e32 v112, v116, v116
	v_fmac_f32_e32 v111, v119, v119
	v_fmac_f32_e32 v112, v117, v117
	v_add_f32_e32 v111, v112, v111
	v_add_f32_e32 v120, v111, v110
	v_lshlrev_b32_e32 v110, 16, v200
	v_and_b32_e32 v111, 0xffff0000, v200
	v_lshlrev_b32_e32 v112, 16, v201
	v_and_b32_e32 v113, 0xffff0000, v201
	v_cvt_pk_bf16_f32 v108, v118, v119
	v_cvt_pk_bf16_f32 v109, v116, v117
	v_lshlrev_b32_e32 v116, 16, v202
	v_and_b32_e32 v117, 0xffff0000, v202
	v_lshlrev_b32_e32 v118, 16, v203
	v_and_b32_e32 v119, 0xffff0000, v203
	v_pk_add_f32 v[104:105], v[104:105], v[112:113]
	v_pk_add_f32 v[102:103], v[102:103], v[110:111]
	v_pk_add_f32 v[110:111], v[100:101], v[118:119]
	v_pk_add_f32 v[100:101], v[98:99], v[116:117]
	v_mul_f32_e32 v98, v103, v103
	v_mul_f32_e32 v99, v104, v104
	v_fmac_f32_e32 v98, v102, v102
	v_fmac_f32_e32 v99, v105, v105
	v_add_f32_e32 v98, v98, v99
	v_mul_f32_e32 v99, v100, v100
	v_mul_f32_e32 v112, v110, v110
	v_fmac_f32_e32 v99, v101, v101
	v_fmac_f32_e32 v112, v111, v111
	v_add_f32_e32 v99, v112, v99
	v_add_f32_e32 v98, v99, v98
	v_add_f32_e32 v112, v120, v98
	ds_bpermute_b32 v113, v114, v112
	v_lshl_add_u64 v[98:99], s[14:15], 0, v[178:179]
	global_store_dwordx4 v[98:99], v[106:109], off
	v_cvt_pk_bf16_f32 v98, v102, v103
	v_cvt_pk_bf16_f32 v99, v104, v105
	s_waitcnt lgkmcnt(0)
	v_add_f32_e32 v104, v112, v113
	ds_bpermute_b32 v105, v115, v104
	v_lshl_add_u64 v[102:103], s[14:15], 0, v[176:177]
	v_cndmask_b32_e64 v1, 0, v1, s[2:3]
	v_cvt_pk_bf16_f32 v100, v100, v101
	v_cvt_pk_bf16_f32 v101, v110, v111
	global_store_dwordx4 v[102:103], v[98:101], off
	v_lshlrev_b32_e32 v102, 16, v144
	v_and_b32_e32 v103, 0xffff0000, v144
	s_waitcnt lgkmcnt(0)
	v_add_f32_e32 v98, v104, v105
	v_cndmask_b32_e64 v1, v1, v98, s[4:5]
	v_lshlrev_b32_e32 v98, 16, v142
	v_and_b32_e32 v99, 0xffff0000, v142
	v_lshlrev_b32_e32 v100, 16, v143
	v_and_b32_e32 v101, 0xffff0000, v143
	v_pk_add_f32 v[94:95], v[94:95], v[98:99]
	v_pk_add_f32 v[96:97], v[96:97], v[100:101]
	v_pk_add_f32 v[100:101], v[90:91], v[102:103]
	v_cvt_pk_bf16_f32 v90, v94, v95
	v_mul_f32_e32 v95, v95, v95
	v_lshlrev_b32_e32 v104, 16, v145
	v_and_b32_e32 v105, 0xffff0000, v145
	v_fmac_f32_e32 v95, v94, v94
	v_mul_f32_e32 v94, v96, v96
	v_pk_add_f32 v[98:99], v[92:93], v[104:105]
	v_fmac_f32_e32 v94, v97, v97
	v_cvt_pk_bf16_f32 v91, v96, v97
	v_add_f32_e32 v94, v95, v94
	v_mul_f32_e32 v95, v100, v100
	v_mul_f32_e32 v96, v98, v98
	v_fmac_f32_e32 v95, v101, v101
	v_fmac_f32_e32 v96, v99, v99
	v_add_f32_e32 v95, v96, v95
	v_add_f32_e32 v102, v95, v94
	v_lshlrev_b32_e32 v94, 16, v138
	v_and_b32_e32 v95, 0xffff0000, v138
	v_lshlrev_b32_e32 v96, 16, v139
	v_and_b32_e32 v97, 0xffff0000, v139
	v_cvt_pk_bf16_f32 v92, v100, v101
	v_cvt_pk_bf16_f32 v93, v98, v99
	v_lshlrev_b32_e32 v98, 16, v140
	v_and_b32_e32 v99, 0xffff0000, v140
	v_lshlrev_b32_e32 v100, 16, v141
	v_and_b32_e32 v101, 0xffff0000, v141
	v_pk_add_f32 v[88:89], v[88:89], v[96:97]
	v_pk_add_f32 v[86:87], v[86:87], v[94:95]
	v_pk_add_f32 v[94:95], v[84:85], v[100:101]
	v_pk_add_f32 v[84:85], v[82:83], v[98:99]
	v_mul_f32_e32 v82, v87, v87
	v_mul_f32_e32 v83, v88, v88
	v_fmac_f32_e32 v82, v86, v86
	v_fmac_f32_e32 v83, v89, v89
	v_add_f32_e32 v82, v82, v83
	v_mul_f32_e32 v83, v84, v84
	v_mul_f32_e32 v96, v94, v94
	v_fmac_f32_e32 v83, v85, v85
	v_fmac_f32_e32 v96, v95, v95
	v_add_f32_e32 v83, v96, v83
	v_add_f32_e32 v82, v83, v82
	v_add_f32_e32 v96, v102, v82
	ds_bpermute_b32 v97, v114, v96
	v_lshl_add_u64 v[82:83], s[14:15], 0, v[174:175]
	global_store_dwordx4 v[82:83], v[90:93], off
	v_cvt_pk_bf16_f32 v82, v86, v87
	v_cvt_pk_bf16_f32 v83, v88, v89
	s_waitcnt lgkmcnt(0)
	v_add_f32_e32 v88, v96, v97
	ds_bpermute_b32 v89, v115, v88
	v_lshl_add_u64 v[86:87], s[14:15], 0, v[172:173]
	v_cvt_pk_bf16_f32 v84, v84, v85
	v_cvt_pk_bf16_f32 v85, v94, v95
	global_store_dwordx4 v[86:87], v[82:85], off
	v_lshlrev_b32_e32 v86, 16, v136
	v_and_b32_e32 v87, 0xffff0000, v136
	s_waitcnt lgkmcnt(0)
	v_add_f32_e32 v82, v88, v89
	v_cndmask_b32_e64 v1, v1, v82, s[6:7]
	v_lshlrev_b32_e32 v82, 16, v134
	v_and_b32_e32 v83, 0xffff0000, v134
	v_lshlrev_b32_e32 v84, 16, v135
	v_and_b32_e32 v85, 0xffff0000, v135
	v_pk_add_f32 v[78:79], v[78:79], v[82:83]
	v_pk_add_f32 v[80:81], v[80:81], v[84:85]
	v_pk_add_f32 v[84:85], v[74:75], v[86:87]
	v_cvt_pk_bf16_f32 v74, v78, v79
	v_mul_f32_e32 v79, v79, v79
	v_lshlrev_b32_e32 v88, 16, v137
	v_and_b32_e32 v89, 0xffff0000, v137
	v_fmac_f32_e32 v79, v78, v78
	v_mul_f32_e32 v78, v80, v80
	v_pk_add_f32 v[82:83], v[76:77], v[88:89]
	v_fmac_f32_e32 v78, v81, v81
	v_cvt_pk_bf16_f32 v75, v80, v81
	v_add_f32_e32 v78, v79, v78
	v_mul_f32_e32 v79, v84, v84
	v_mul_f32_e32 v80, v82, v82
	v_fmac_f32_e32 v79, v85, v85
	v_fmac_f32_e32 v80, v83, v83
	v_add_f32_e32 v79, v80, v79
	v_add_f32_e32 v86, v79, v78
	v_lshlrev_b32_e32 v78, 16, v130
	v_and_b32_e32 v79, 0xffff0000, v130
	v_lshlrev_b32_e32 v80, 16, v131
	v_and_b32_e32 v81, 0xffff0000, v131
	v_cvt_pk_bf16_f32 v76, v84, v85
	v_cvt_pk_bf16_f32 v77, v82, v83
	v_lshlrev_b32_e32 v82, 16, v132
	v_and_b32_e32 v83, 0xffff0000, v132
	v_lshlrev_b32_e32 v84, 16, v133
	v_and_b32_e32 v85, 0xffff0000, v133
	v_pk_add_f32 v[72:73], v[72:73], v[80:81]
	v_pk_add_f32 v[70:71], v[70:71], v[78:79]
	v_pk_add_f32 v[78:79], v[68:69], v[84:85]
	v_pk_add_f32 v[68:69], v[66:67], v[82:83]
	v_mul_f32_e32 v66, v71, v71
	v_mul_f32_e32 v67, v72, v72
	v_fmac_f32_e32 v66, v70, v70
	v_fmac_f32_e32 v67, v73, v73
	v_add_f32_e32 v66, v66, v67
	v_mul_f32_e32 v67, v68, v68
	v_mul_f32_e32 v80, v78, v78
	v_fmac_f32_e32 v67, v69, v69
	v_fmac_f32_e32 v80, v79, v79
	v_add_f32_e32 v67, v80, v67
	v_add_f32_e32 v66, v67, v66
	v_add_f32_e32 v80, v86, v66
	ds_bpermute_b32 v81, v114, v80
	v_lshl_add_u64 v[66:67], s[14:15], 0, v[168:169]
	global_store_dwordx4 v[66:67], v[74:77], off
	v_cvt_pk_bf16_f32 v66, v70, v71
	v_cvt_pk_bf16_f32 v67, v72, v73
	s_waitcnt lgkmcnt(0)
	v_add_f32_e32 v72, v80, v81
	ds_bpermute_b32 v73, v115, v72
	v_lshl_add_u64 v[70:71], s[14:15], 0, v[170:171]
	v_cvt_pk_bf16_f32 v68, v68, v69
	v_cvt_pk_bf16_f32 v69, v78, v79
	global_store_dwordx4 v[70:71], v[66:69], off
	v_ashrrev_i32_e32 v163, 31, v162
	s_andn2_b64 vcc, exec, s[10:11]
	s_waitcnt lgkmcnt(0)
	v_add_f32_e32 v66, v72, v73
	v_cndmask_b32_e64 v1, v1, v66, s[8:9]
	v_lshl_add_u64 v[66:67], v[162:163], 2, s[16:17]
	global_atomic_add_f32 v[66:67], v1, off
	v_add_u32_e32 v66, 0x80, v166
	v_ashrrev_i32_e32 v67, 31, v66
	v_lshlrev_b64 v[66:67], 11, v[66:67]
	v_lshl_add_u64 v[66:67], v[66:67], 0, v[164:165]
	v_lshlrev_b64 v[110:111], 1, v[66:67]
	v_lshl_add_u64 v[66:67], s[12:13], 0, v[110:111]
	v_or_b32_e32 v112, 0x100, v110
	v_mov_b32_e32 v113, v111
	v_lshl_add_u64 v[66:67], s[12:13], 0, v[112:113]
	v_add_u32_e32 v66, 0x90, v166
	v_ashrrev_i32_e32 v67, 31, v66
	v_lshlrev_b64 v[66:67], 11, v[66:67]
	v_lshl_add_u64 v[66:67], v[66:67], 0, v[164:165]
	v_lshlrev_b64 v[92:93], 1, v[66:67]
	v_lshl_add_u64 v[66:67], s[12:13], 0, v[92:93]
	v_or_b32_e32 v90, 0x100, v92
	v_mov_b32_e32 v91, v93
	v_lshl_add_u64 v[68:69], s[12:13], 0, v[90:91]
	v_add_u32_e32 v66, 0xa0, v166
	v_ashrrev_i32_e32 v67, 31, v66
	v_lshlrev_b64 v[66:67], 11, v[66:67]
	v_lshl_add_u64 v[66:67], v[66:67], 0, v[164:165]
	v_lshlrev_b64 v[88:89], 1, v[66:67]
	v_lshl_add_u64 v[66:67], s[12:13], 0, v[88:89]
	v_or_b32_e32 v86, 0x100, v88
	v_mov_b32_e32 v87, v89
	v_lshl_add_u64 v[68:69], s[12:13], 0, v[86:87]
	v_add_u32_e32 v66, 0xb0, v166
	v_ashrrev_i32_e32 v67, 31, v66
	v_lshlrev_b64 v[66:67], 11, v[66:67]
	v_lshl_add_u64 v[66:67], v[66:67], 0, v[164:165]
	v_lshlrev_b64 v[84:85], 1, v[66:67]
	v_or_b32_e32 v82, 0x100, v84
	v_mov_b32_e32 v83, v85
	v_lshl_add_u64 v[66:67], s[12:13], 0, v[84:85]
	v_lshl_add_u64 v[68:69], s[12:13], 0, v[82:83]
	s_nop 0
	s_mov_b64 s[10:11], -1
	s_waitcnt vmcnt(9)
	v_lshlrev_b32_e32 v116, 16, v220
	v_and_b32_e32 v117, 0xffff0000, v220
	v_lshlrev_b32_e32 v94, 16, v221
	v_and_b32_e32 v95, 0xffff0000, v221
	v_pk_add_f32 v[62:63], v[62:63], v[116:117]
	v_lshlrev_b32_e32 v118, 16, v222
	v_and_b32_e32 v119, 0xffff0000, v222
	v_lshlrev_b32_e32 v96, 16, v223
	v_and_b32_e32 v97, 0xffff0000, v223
	v_pk_add_f32 v[64:65], v[64:65], v[94:95]
	v_mul_f32_e32 v1, v63, v63
	v_pk_add_f32 v[94:95], v[60:61], v[96:97]
	v_pk_add_f32 v[96:97], v[58:59], v[118:119]
	v_cvt_pk_bf16_f32 v58, v62, v63
	v_fmac_f32_e32 v1, v62, v62
	v_mul_f32_e32 v62, v64, v64
	v_fmac_f32_e32 v62, v65, v65
	v_add_f32_e32 v1, v1, v62
	v_mul_f32_e32 v62, v96, v96
	v_mul_f32_e32 v63, v94, v94
	v_fmac_f32_e32 v62, v97, v97
	v_fmac_f32_e32 v63, v95, v95
	v_add_f32_e32 v62, v63, v62
	v_cvt_pk_bf16_f32 v59, v64, v65
	v_add_f32_e32 v1, v62, v1
	s_nop 0
	v_lshlrev_b32_e32 v62, 16, v224
	v_and_b32_e32 v63, 0xffff0000, v224
	v_lshlrev_b32_e32 v64, 16, v225
	v_and_b32_e32 v65, 0xffff0000, v225
	v_cvt_pk_bf16_f32 v60, v96, v97
	v_cvt_pk_bf16_f32 v61, v94, v95
	v_lshlrev_b32_e32 v94, 16, v226
	v_and_b32_e32 v95, 0xffff0000, v226
	v_lshlrev_b32_e32 v96, 16, v227
	v_and_b32_e32 v97, 0xffff0000, v227
	v_pk_add_f32 v[56:57], v[56:57], v[64:65]
	v_pk_add_f32 v[54:55], v[54:55], v[62:63]
	v_pk_add_f32 v[62:63], v[52:53], v[96:97]
	v_pk_add_f32 v[52:53], v[50:51], v[94:95]
	v_mul_f32_e32 v50, v55, v55
	v_mul_f32_e32 v51, v56, v56
	v_fmac_f32_e32 v50, v54, v54
	v_fmac_f32_e32 v51, v57, v57
	v_add_f32_e32 v50, v50, v51
	v_mul_f32_e32 v51, v52, v52
	v_mul_f32_e32 v64, v62, v62
	v_fmac_f32_e32 v51, v53, v53
	v_fmac_f32_e32 v64, v63, v63
	v_add_f32_e32 v51, v64, v51
	v_add_f32_e32 v50, v51, v50
	v_add_f32_e32 v1, v1, v50
	ds_bpermute_b32 v64, v114, v1
	v_lshl_add_u64 v[50:51], s[14:15], 0, v[110:111]
	global_store_dwordx4 v[50:51], v[58:61], off
	v_cvt_pk_bf16_f32 v50, v54, v55
	v_cvt_pk_bf16_f32 v51, v56, v57
	s_waitcnt lgkmcnt(0)
	v_add_f32_e32 v1, v1, v64
	ds_bpermute_b32 v56, v115, v1
	v_lshl_add_u64 v[54:55], s[14:15], 0, v[112:113]
	v_cvt_pk_bf16_f32 v52, v52, v53
	v_cvt_pk_bf16_f32 v53, v62, v63
	global_store_dwordx4 v[54:55], v[50:53], off
	s_nop 0
	v_lshlrev_b32_e32 v54, 16, v230
	v_and_b32_e32 v55, 0xffff0000, v230
	v_lshlrev_b32_e32 v50, 16, v228
	v_and_b32_e32 v51, 0xffff0000, v228
	v_lshlrev_b32_e32 v52, 16, v229
	v_and_b32_e32 v53, 0xffff0000, v229
	v_pk_add_f32 v[46:47], v[46:47], v[50:51]
	v_pk_add_f32 v[48:49], v[48:49], v[52:53]
	v_pk_add_f32 v[52:53], v[42:43], v[54:55]
	v_cvt_pk_bf16_f32 v42, v46, v47
	v_mul_f32_e32 v47, v47, v47
	s_waitcnt lgkmcnt(0)
	v_add_f32_e32 v1, v1, v56
	v_lshlrev_b32_e32 v56, 16, v231
	v_and_b32_e32 v57, 0xffff0000, v231
	v_fmac_f32_e32 v47, v46, v46
	v_mul_f32_e32 v46, v48, v48
	v_pk_add_f32 v[50:51], v[44:45], v[56:57]
	v_fmac_f32_e32 v46, v49, v49
	v_cvt_pk_bf16_f32 v43, v48, v49
	v_add_f32_e32 v46, v47, v46
	v_mul_f32_e32 v47, v52, v52
	v_mul_f32_e32 v48, v50, v50
	v_fmac_f32_e32 v47, v53, v53
	v_fmac_f32_e32 v48, v51, v51
	v_add_f32_e32 v47, v48, v47
	v_add_f32_e32 v54, v47, v46
	s_nop 0
	v_lshlrev_b32_e32 v46, 16, v232
	v_and_b32_e32 v47, 0xffff0000, v232
	v_lshlrev_b32_e32 v48, 16, v233
	v_and_b32_e32 v49, 0xffff0000, v233
	v_cvt_pk_bf16_f32 v44, v52, v53
	v_cvt_pk_bf16_f32 v45, v50, v51
	v_lshlrev_b32_e32 v50, 16, v234
	v_and_b32_e32 v51, 0xffff0000, v234
	v_lshlrev_b32_e32 v52, 16, v235
	v_and_b32_e32 v53, 0xffff0000, v235
	v_pk_add_f32 v[40:41], v[40:41], v[48:49]
	v_pk_add_f32 v[38:39], v[38:39], v[46:47]
	v_pk_add_f32 v[46:47], v[36:37], v[52:53]
	v_pk_add_f32 v[36:37], v[34:35], v[50:51]
	v_mul_f32_e32 v34, v39, v39
	v_mul_f32_e32 v35, v40, v40
	v_fmac_f32_e32 v34, v38, v38
	v_fmac_f32_e32 v35, v41, v41
	v_add_f32_e32 v34, v34, v35
	v_mul_f32_e32 v35, v36, v36
	v_mul_f32_e32 v48, v46, v46
	v_fmac_f32_e32 v35, v37, v37
	v_fmac_f32_e32 v48, v47, v47
	v_add_f32_e32 v35, v48, v35
	v_add_f32_e32 v34, v35, v34
	v_add_f32_e32 v48, v54, v34
	ds_bpermute_b32 v49, v114, v48
	v_lshl_add_u64 v[34:35], s[14:15], 0, v[92:93]
	global_store_dwordx4 v[34:35], v[42:45], off
	v_cvt_pk_bf16_f32 v34, v38, v39
	v_cvt_pk_bf16_f32 v35, v40, v41
	s_waitcnt lgkmcnt(0)
	v_add_f32_e32 v40, v48, v49
	ds_bpermute_b32 v41, v115, v40
	v_lshl_add_u64 v[38:39], s[14:15], 0, v[90:91]
	v_cndmask_b32_e64 v1, 0, v1, s[2:3]
	v_cvt_pk_bf16_f32 v36, v36, v37
	v_cvt_pk_bf16_f32 v37, v46, v47
	global_store_dwordx4 v[38:39], v[34:37], off
	s_nop 0
	v_lshlrev_b32_e32 v38, 16, v238
	v_and_b32_e32 v39, 0xffff0000, v238
	s_waitcnt lgkmcnt(0)
	v_add_f32_e32 v34, v40, v41
	v_cndmask_b32_e64 v1, v1, v34, s[4:5]
	v_lshlrev_b32_e32 v34, 16, v236
	v_and_b32_e32 v35, 0xffff0000, v236
	v_lshlrev_b32_e32 v36, 16, v237
	v_and_b32_e32 v37, 0xffff0000, v237
	v_pk_add_f32 v[30:31], v[30:31], v[34:35]
	v_pk_add_f32 v[32:33], v[32:33], v[36:37]
	v_pk_add_f32 v[36:37], v[26:27], v[38:39]
	v_cvt_pk_bf16_f32 v26, v30, v31
	v_mul_f32_e32 v31, v31, v31
	v_lshlrev_b32_e32 v40, 16, v239
	v_and_b32_e32 v41, 0xffff0000, v239
	v_fmac_f32_e32 v31, v30, v30
	v_mul_f32_e32 v30, v32, v32
	v_pk_add_f32 v[34:35], v[28:29], v[40:41]
	v_fmac_f32_e32 v30, v33, v33
	v_cvt_pk_bf16_f32 v27, v32, v33
	v_add_f32_e32 v30, v31, v30
	v_mul_f32_e32 v31, v36, v36
	v_mul_f32_e32 v32, v34, v34
	v_fmac_f32_e32 v31, v37, v37
	v_fmac_f32_e32 v32, v35, v35
	v_add_f32_e32 v31, v32, v31
	v_add_f32_e32 v38, v31, v30
	s_nop 0
	v_lshlrev_b32_e32 v30, 16, v240
	v_and_b32_e32 v31, 0xffff0000, v240
	v_lshlrev_b32_e32 v32, 16, v241
	v_and_b32_e32 v33, 0xffff0000, v241
	v_cvt_pk_bf16_f32 v28, v36, v37
	v_cvt_pk_bf16_f32 v29, v34, v35
	v_lshlrev_b32_e32 v34, 16, v242
	v_and_b32_e32 v35, 0xffff0000, v242
	v_lshlrev_b32_e32 v36, 16, v243
	v_and_b32_e32 v37, 0xffff0000, v243
	v_pk_add_f32 v[24:25], v[24:25], v[32:33]
	v_pk_add_f32 v[22:23], v[22:23], v[30:31]
	v_pk_add_f32 v[30:31], v[20:21], v[36:37]
	v_pk_add_f32 v[20:21], v[18:19], v[34:35]
	v_mul_f32_e32 v18, v23, v23
	v_mul_f32_e32 v19, v24, v24
	v_fmac_f32_e32 v18, v22, v22
	v_fmac_f32_e32 v19, v25, v25
	v_add_f32_e32 v18, v18, v19
	v_mul_f32_e32 v19, v20, v20
	v_mul_f32_e32 v32, v30, v30
	v_fmac_f32_e32 v19, v21, v21
	v_fmac_f32_e32 v32, v31, v31
	v_add_f32_e32 v19, v32, v19
	v_add_f32_e32 v18, v19, v18
	v_add_f32_e32 v32, v38, v18
	ds_bpermute_b32 v33, v114, v32
	v_lshl_add_u64 v[18:19], s[14:15], 0, v[88:89]
	global_store_dwordx4 v[18:19], v[26:29], off
	v_cvt_pk_bf16_f32 v18, v22, v23
	v_cvt_pk_bf16_f32 v19, v24, v25
	s_waitcnt lgkmcnt(0)
	v_add_f32_e32 v24, v32, v33
	ds_bpermute_b32 v25, v115, v24
	v_lshl_add_u64 v[22:23], s[14:15], 0, v[86:87]
	v_cvt_pk_bf16_f32 v20, v20, v21
	v_cvt_pk_bf16_f32 v21, v30, v31
	global_store_dwordx4 v[22:23], v[18:21], off
	s_nop 0
	v_lshlrev_b32_e32 v22, 16, v246
	v_and_b32_e32 v23, 0xffff0000, v246
	s_waitcnt lgkmcnt(0)
	v_add_f32_e32 v18, v24, v25
	v_cndmask_b32_e64 v1, v1, v18, s[6:7]
	v_lshlrev_b32_e32 v18, 16, v244
	v_and_b32_e32 v19, 0xffff0000, v244
	v_lshlrev_b32_e32 v20, 16, v245
	v_and_b32_e32 v21, 0xffff0000, v245
	v_pk_add_f32 v[14:15], v[14:15], v[18:19]
	v_pk_add_f32 v[16:17], v[16:17], v[20:21]
	v_pk_add_f32 v[20:21], v[10:11], v[22:23]
	v_cvt_pk_bf16_f32 v10, v14, v15
	v_mul_f32_e32 v15, v15, v15
	v_lshlrev_b32_e32 v24, 16, v247
	v_and_b32_e32 v25, 0xffff0000, v247
	v_fmac_f32_e32 v15, v14, v14
	v_mul_f32_e32 v14, v16, v16
	v_pk_add_f32 v[18:19], v[12:13], v[24:25]
	v_fmac_f32_e32 v14, v17, v17
	v_cvt_pk_bf16_f32 v11, v16, v17
	v_add_f32_e32 v14, v15, v14
	v_mul_f32_e32 v15, v20, v20
	v_mul_f32_e32 v16, v18, v18
	v_fmac_f32_e32 v15, v21, v21
	v_fmac_f32_e32 v16, v19, v19
	v_add_f32_e32 v15, v16, v15
	v_add_f32_e32 v22, v15, v14
	s_nop 0
	v_lshlrev_b32_e32 v14, 16, v248
	v_and_b32_e32 v15, 0xffff0000, v248
	v_lshlrev_b32_e32 v16, 16, v249
	v_and_b32_e32 v17, 0xffff0000, v249
	v_cvt_pk_bf16_f32 v12, v20, v21
	v_cvt_pk_bf16_f32 v13, v18, v19
	v_lshlrev_b32_e32 v18, 16, v250
	v_and_b32_e32 v19, 0xffff0000, v250
	v_lshlrev_b32_e32 v20, 16, v251
	v_and_b32_e32 v21, 0xffff0000, v251
	v_pk_add_f32 v[8:9], v[8:9], v[16:17]
	v_pk_add_f32 v[6:7], v[6:7], v[14:15]
	v_pk_add_f32 v[14:15], v[4:5], v[20:21]
	v_pk_add_f32 v[4:5], v[2:3], v[18:19]
	v_mul_f32_e32 v2, v7, v7
	v_mul_f32_e32 v3, v8, v8
	v_fmac_f32_e32 v2, v6, v6
	v_fmac_f32_e32 v3, v9, v9
	v_add_f32_e32 v2, v2, v3
	v_mul_f32_e32 v3, v4, v4
	v_mul_f32_e32 v16, v14, v14
	v_fmac_f32_e32 v3, v5, v5
	v_fmac_f32_e32 v16, v15, v15
	v_add_f32_e32 v3, v16, v3
	v_add_f32_e32 v2, v3, v2
	v_add_f32_e32 v16, v22, v2
	ds_bpermute_b32 v17, v114, v16
	v_lshl_add_u64 v[2:3], s[14:15], 0, v[84:85]
	global_store_dwordx4 v[2:3], v[10:13], off
	v_cvt_pk_bf16_f32 v2, v6, v7
	v_cvt_pk_bf16_f32 v3, v8, v9
	s_waitcnt lgkmcnt(0)
	v_add_f32_e32 v8, v16, v17
	ds_bpermute_b32 v9, v115, v8
	v_lshl_add_u64 v[6:7], s[14:15], 0, v[82:83]
	v_cvt_pk_bf16_f32 v4, v4, v5
	v_cvt_pk_bf16_f32 v5, v14, v15
	global_store_dwordx4 v[6:7], v[2:5], off
	s_waitcnt lgkmcnt(0)
	s_nop 0
	v_add_f32_e32 v2, v8, v9
	v_cndmask_b32_e64 v1, v1, v2, s[8:9]
	v_add_u32_e32 v2, 0x80, v162
	v_ashrrev_i32_e32 v3, 31, v2
	v_lshl_add_u64 v[2:3], v[2:3], 2, s[16:17]
	global_atomic_add_f32 v[2:3], v1, off
	s_cbranch_vccnz .LBB0_1400
	s_andn2_b64 vcc, exec, s[0:1]
	s_cbranch_vccnz .LBB0_1399
	s_barrier
	s_branch .LBB0_1399

.LBB0_1569:
	s_andn2_b64 vcc, exec, s[12:13]
	s_cbranch_vccnz .LBB0_1571
	v_lshl_add_u32 v146, s44, 8, v148
	v_lshl_or_b32 v144, s45, 8, v150
	v_ashrrev_i32_e32 v147, 31, v146
	v_ashrrev_i32_e32 v145, 31, v144
	v_lshlrev_b64 v[154:155], 11, v[146:147]
	v_or_b32_e32 v162, 16, v146
	v_lshl_add_u64 v[178:179], v[154:155], 0, v[144:145]
	v_ashrrev_i32_e32 v163, 31, v162
	v_lshlrev_b64 v[158:159], 1, v[178:179]
	v_lshlrev_b64 v[162:163], 11, v[162:163]
	v_lshl_add_u64 v[154:155], s[6:7], 0, v[158:159]
	s_add_u32 s98, s6, 0x80000
	s_addc_u32 s99, s7, 0
	global_load_dwordx4 v[216:219], v158, s[98:99]
	s_nop 1
	v_or_b32_e32 v158, 0x100, v158
	v_lshl_add_u64 v[180:181], v[162:163], 0, v[144:145]
	global_load_dwordx4 v[220:223], v158, s[98:99]
	s_nop 1
	v_lshl_add_u64 v[158:159], s[6:7], 0, v[158:159]
	v_lshlrev_b64 v[166:167], 1, v[180:181]
	global_load_dwordx4 v[154:157], v[154:155], off
	v_lshl_add_u64 v[162:163], s[6:7], 0, v[166:167]
	global_load_dwordx4 v[158:161], v[158:159], off
	v_or_b32_e32 v170, 32, v146
	global_load_dwordx4 v[162:165], v[162:163], off
	global_load_dwordx4 v[224:227], v166, s[98:99]
	s_nop 1
	v_or_b32_e32 v166, 0x100, v166
	v_ashrrev_i32_e32 v171, 31, v170
	global_load_dwordx4 v[228:231], v166, s[98:99]
	s_nop 1
	v_lshl_add_u64 v[166:167], s[6:7], 0, v[166:167]
	v_lshlrev_b64 v[170:171], 11, v[170:171]
	global_load_dwordx4 v[166:169], v[166:167], off
	v_lshl_add_u64 v[186:187], v[170:171], 0, v[144:145]
	v_lshlrev_b64 v[174:175], 1, v[186:187]
	v_lshl_add_u64 v[170:171], s[6:7], 0, v[174:175]
	v_or_b32_e32 v182, 48, v146
	global_load_dwordx4 v[170:173], v[170:171], off
	v_ashrrev_i32_e32 v183, 31, v182
	global_load_dwordx4 v[232:235], v174, s[98:99]
	s_nop 1
	v_or_b32_e32 v174, 0x100, v174
	v_lshlrev_b64 v[182:183], 11, v[182:183]
	global_load_dwordx4 v[236:239], v174, s[98:99]
	s_nop 1
	v_lshl_add_u64 v[174:175], s[6:7], 0, v[174:175]
	v_lshl_add_u64 v[188:189], v[182:183], 0, v[144:145]
	global_load_dwordx4 v[174:177], v[174:175], off
	v_lshl_add_u64 v[190:191], v[178:179], 2, s[50:51]
	v_lshlrev_b64 v[178:179], 1, v[188:189]
	v_lshl_add_u64 v[192:193], v[180:181], 2, s[50:51]
	v_or_b32_e32 v180, 0x100, v178
	v_mov_b32_e32 v181, v179
	v_lshl_add_u64 v[182:183], s[6:7], 0, v[178:179]
	global_load_dwordx4 v[240:243], v180, s[98:99]
	global_load_dwordx4 v[244:247], v178, s[98:99]
	s_nop 1
	v_lshl_add_u64 v[178:179], s[6:7], 0, v[180:181]
	global_load_dwordx4 v[178:181], v[178:179], off
	s_nop 0
	global_load_dwordx4 v[182:185], v[182:183], off
	s_waitcnt vmcnt(0)
	v_lshlrev_b32_e32 v196, 16, v154
	v_and_b32_e32 v197, 0xffff0000, v154
	v_lshlrev_b32_e32 v154, 16, v155
	v_and_b32_e32 v155, 0xffff0000, v155
	v_lshlrev_b32_e32 v198, 16, v160
	v_and_b32_e32 v199, 0xffff0000, v160
	v_lshlrev_b32_e32 v160, 16, v161
	v_and_b32_e32 v161, 0xffff0000, v161
	v_lshlrev_b32_e32 v200, 16, v158
	v_and_b32_e32 v201, 0xffff0000, v158
	v_lshlrev_b32_e32 v158, 16, v159
	v_and_b32_e32 v159, 0xffff0000, v159
	v_lshlrev_b32_e32 v194, 16, v156
	v_and_b32_e32 v195, 0xffff0000, v156
	v_lshlrev_b32_e32 v156, 16, v157
	v_and_b32_e32 v157, 0xffff0000, v157
	v_pk_fma_f32 v[126:127], v[126:127], 0.5, v[154:155] op_sel_hi:[1,0,1]
	v_pk_fma_f32 v[114:115], v[114:115], 0.5, v[160:161] op_sel_hi:[1,0,1]
	v_pk_fma_f32 v[118:119], v[118:119], 0.5, v[158:159] op_sel_hi:[1,0,1]
	v_lshlrev_b32_e32 v154, 16, v164
	v_and_b32_e32 v155, 0xffff0000, v164
	v_lshlrev_b32_e32 v158, 16, v162
	v_and_b32_e32 v159, 0xffff0000, v162
	v_lshlrev_b32_e32 v160, 16, v163
	v_and_b32_e32 v161, 0xffff0000, v163
	v_pk_fma_f32 v[122:123], v[122:123], 0.5, v[156:157] op_sel_hi:[1,0,1]
	v_pk_fma_f32 v[124:125], v[124:125], 0.5, v[196:197] op_sel_hi:[1,0,1]
	v_lshlrev_b32_e32 v156, 16, v165
	v_and_b32_e32 v157, 0xffff0000, v165
	v_pk_fma_f32 v[104:105], v[104:105], 0.5, v[154:155] op_sel_hi:[1,0,1]
	v_pk_fma_f32 v[110:111], v[110:111], 0.5, v[160:161] op_sel_hi:[1,0,1]
	v_pk_fma_f32 v[108:109], v[108:109], 0.5, v[158:159] op_sel_hi:[1,0,1]
	v_pk_fma_f32 v[120:121], v[120:121], 0.5, v[194:195] op_sel_hi:[1,0,1]
	v_pk_fma_f32 v[112:113], v[112:113], 0.5, v[198:199] op_sel_hi:[1,0,1]
	v_pk_fma_f32 v[116:117], v[116:117], 0.5, v[200:201] op_sel_hi:[1,0,1]
	global_store_dwordx4 v[190:191], v[124:127], off
	global_store_dwordx4 v[190:191], v[120:123], off offset:16
	global_store_dwordx4 v[190:191], v[116:119], off offset:512
	global_store_dwordx4 v[190:191], v[112:115], off offset:528
	v_pk_fma_f32 v[106:107], v[106:107], 0.5, v[156:157] op_sel_hi:[1,0,1]
	global_store_dwordx4 v[192:193], v[108:111], off
	global_store_dwordx4 v[192:193], v[104:107], off offset:16
	v_lshlrev_b32_e32 v162, 16, v168
	v_and_b32_e32 v163, 0xffff0000, v168
	v_lshlrev_b32_e32 v104, 16, v169
	v_and_b32_e32 v105, 0xffff0000, v169
	v_pk_fma_f32 v[102:103], v[102:103], 0.5, v[104:105] op_sel_hi:[1,0,1]
	v_lshlrev_b32_e32 v104, 16, v166
	v_and_b32_e32 v105, 0xffff0000, v166
	v_lshlrev_b32_e32 v106, 16, v167
	v_and_b32_e32 v107, 0xffff0000, v167
	v_pk_fma_f32 v[100:101], v[100:101], 0.5, v[162:163] op_sel_hi:[1,0,1]
	v_pk_fma_f32 v[98:99], v[98:99], 0.5, v[106:107] op_sel_hi:[1,0,1]
	v_pk_fma_f32 v[96:97], v[96:97], 0.5, v[104:105] op_sel_hi:[1,0,1]
	global_store_dwordx4 v[192:193], v[96:99], off offset:512
	global_store_dwordx4 v[192:193], v[100:103], off offset:528
	s_nop 0
	v_lshlrev_b32_e32 v98, 16, v172
	v_and_b32_e32 v99, 0xffff0000, v172
	v_lshlrev_b32_e32 v100, 16, v173
	v_and_b32_e32 v101, 0xffff0000, v173
	v_pk_fma_f32 v[94:95], v[94:95], 0.5, v[100:101] op_sel_hi:[1,0,1]
	v_pk_fma_f32 v[92:93], v[92:93], 0.5, v[98:99] op_sel_hi:[1,0,1]
	v_lshlrev_b32_e32 v98, 16, v170
	v_and_b32_e32 v99, 0xffff0000, v170
	v_lshlrev_b32_e32 v100, 16, v171
	v_and_b32_e32 v101, 0xffff0000, v171
	v_lshl_add_u64 v[96:97], v[186:187], 2, s[50:51]
	v_pk_fma_f32 v[90:91], v[90:91], 0.5, v[100:101] op_sel_hi:[1,0,1]
	v_pk_fma_f32 v[88:89], v[88:89], 0.5, v[98:99] op_sel_hi:[1,0,1]
	global_store_dwordx4 v[96:97], v[88:91], off
	global_store_dwordx4 v[96:97], v[92:95], off offset:16
	s_nop 0
	v_lshlrev_b32_e32 v88, 16, v176
	v_and_b32_e32 v89, 0xffff0000, v176
	v_lshlrev_b32_e32 v90, 16, v177
	v_and_b32_e32 v91, 0xffff0000, v177
	v_pk_fma_f32 v[86:87], v[86:87], 0.5, v[90:91] op_sel_hi:[1,0,1]
	v_pk_fma_f32 v[84:85], v[84:85], 0.5, v[88:89] op_sel_hi:[1,0,1]
	v_lshlrev_b32_e32 v88, 16, v174
	v_and_b32_e32 v89, 0xffff0000, v174
	v_lshlrev_b32_e32 v90, 16, v175
	v_and_b32_e32 v91, 0xffff0000, v175
	v_pk_fma_f32 v[82:83], v[82:83], 0.5, v[90:91] op_sel_hi:[1,0,1]
	v_pk_fma_f32 v[80:81], v[80:81], 0.5, v[88:89] op_sel_hi:[1,0,1]
	global_store_dwordx4 v[96:97], v[80:83], off offset:512
	global_store_dwordx4 v[96:97], v[84:87], off offset:528
	s_nop 0
	v_lshlrev_b32_e32 v82, 16, v184
	v_and_b32_e32 v83, 0xffff0000, v184
	v_lshlrev_b32_e32 v84, 16, v185
	v_and_b32_e32 v85, 0xffff0000, v185
	v_pk_fma_f32 v[78:79], v[78:79], 0.5, v[84:85] op_sel_hi:[1,0,1]
	v_pk_fma_f32 v[76:77], v[76:77], 0.5, v[82:83] op_sel_hi:[1,0,1]
	v_lshlrev_b32_e32 v82, 16, v182
	v_and_b32_e32 v83, 0xffff0000, v182
	v_lshlrev_b32_e32 v84, 16, v183
	v_and_b32_e32 v85, 0xffff0000, v183
	v_lshl_add_u64 v[80:81], v[188:189], 2, s[50:51]
	v_pk_fma_f32 v[74:75], v[74:75], 0.5, v[84:85] op_sel_hi:[1,0,1]
	v_pk_fma_f32 v[72:73], v[72:73], 0.5, v[82:83] op_sel_hi:[1,0,1]
	global_store_dwordx4 v[80:81], v[72:75], off
	global_store_dwordx4 v[80:81], v[76:79], off offset:16
	s_nop 0
	v_lshlrev_b32_e32 v72, 16, v180
	v_and_b32_e32 v73, 0xffff0000, v180
	v_lshlrev_b32_e32 v74, 16, v181
	v_and_b32_e32 v75, 0xffff0000, v181
	v_pk_fma_f32 v[70:71], v[70:71], 0.5, v[74:75] op_sel_hi:[1,0,1]
	v_pk_fma_f32 v[68:69], v[68:69], 0.5, v[72:73] op_sel_hi:[1,0,1]
	v_lshlrev_b32_e32 v72, 16, v178
	v_and_b32_e32 v73, 0xffff0000, v178
	v_lshlrev_b32_e32 v74, 16, v179
	v_and_b32_e32 v75, 0xffff0000, v179
	v_pk_fma_f32 v[66:67], v[66:67], 0.5, v[74:75] op_sel_hi:[1,0,1]
	v_pk_fma_f32 v[64:65], v[64:65], 0.5, v[72:73] op_sel_hi:[1,0,1]
	global_store_dwordx4 v[80:81], v[64:67], off offset:512
	global_store_dwordx4 v[80:81], v[68:71], off offset:528
	s_nop 0
	v_add_u32_e32 v64, 0x80, v146
	v_ashrrev_i32_e32 v65, 31, v64
	v_lshlrev_b64 v[64:65], 11, v[64:65]
	v_lshl_add_u64 v[96:97], v[64:65], 0, v[144:145]
	v_lshlrev_b64 v[64:65], 1, v[96:97]
	v_lshl_add_u64 v[66:67], s[6:7], 0, v[64:65]
	v_or_b32_e32 v64, 0x100, v64
	v_lshl_add_u64 v[64:65], s[6:7], 0, v[64:65]
	v_add_u32_e32 v64, 0x90, v146
	v_ashrrev_i32_e32 v65, 31, v64
	v_lshlrev_b64 v[64:65], 11, v[64:65]
	v_lshl_add_u64 v[98:99], v[64:65], 0, v[144:145]
	v_lshlrev_b64 v[64:65], 1, v[98:99]
	v_lshl_add_u64 v[66:67], s[6:7], 0, v[64:65]
	v_or_b32_e32 v64, 0x100, v64
	v_lshl_add_u64 v[64:65], s[6:7], 0, v[64:65]
	v_add_u32_e32 v64, 0xa0, v146
	v_ashrrev_i32_e32 v65, 31, v64
	v_lshlrev_b64 v[64:65], 11, v[64:65]
	v_lshl_add_u64 v[100:101], v[64:65], 0, v[144:145]
	v_lshlrev_b64 v[64:65], 1, v[100:101]
	v_lshl_add_u64 v[66:67], s[6:7], 0, v[64:65]
	v_or_b32_e32 v64, 0x100, v64
	v_lshl_add_u64 v[64:65], s[6:7], 0, v[64:65]
	v_add_u32_e32 v64, 0xb0, v146
	v_ashrrev_i32_e32 v65, 31, v64
	v_lshlrev_b64 v[64:65], 11, v[64:65]
	v_lshl_add_u64 v[102:103], v[64:65], 0, v[144:145]
	v_lshlrev_b64 v[64:65], 1, v[102:103]
	v_or_b32_e32 v66, 0x100, v64
	v_mov_b32_e32 v67, v65
	v_lshl_add_u64 v[66:67], s[6:7], 0, v[66:67]
	v_lshl_add_u64 v[92:93], s[6:7], 0, v[64:65]
	s_nop 0
	v_lshl_add_u64 v[96:97], v[96:97], 2, s[50:51]
	s_nop 0
	v_lshlrev_b32_e32 v104, 16, v218
	v_and_b32_e32 v105, 0xffff0000, v218
	v_lshlrev_b32_e32 v70, 16, v219
	v_and_b32_e32 v71, 0xffff0000, v219
	v_pk_fma_f32 v[62:63], v[62:63], 0.5, v[70:71] op_sel_hi:[1,0,1]
	v_lshlrev_b32_e32 v70, 16, v216
	v_and_b32_e32 v71, 0xffff0000, v216
	v_lshlrev_b32_e32 v68, 16, v217
	v_and_b32_e32 v69, 0xffff0000, v217
	v_pk_fma_f32 v[58:59], v[58:59], 0.5, v[68:69] op_sel_hi:[1,0,1]
	v_pk_fma_f32 v[56:57], v[56:57], 0.5, v[70:71] op_sel_hi:[1,0,1]
	v_pk_fma_f32 v[60:61], v[60:61], 0.5, v[104:105] op_sel_hi:[1,0,1]
	global_store_dwordx4 v[96:97], v[56:59], off
	global_store_dwordx4 v[96:97], v[60:63], off offset:16
	s_nop 0
	v_lshlrev_b32_e32 v56, 16, v222
	v_and_b32_e32 v57, 0xffff0000, v222
	v_lshlrev_b32_e32 v58, 16, v223
	v_and_b32_e32 v59, 0xffff0000, v223
	v_pk_fma_f32 v[54:55], v[54:55], 0.5, v[58:59] op_sel_hi:[1,0,1]
	v_pk_fma_f32 v[52:53], v[52:53], 0.5, v[56:57] op_sel_hi:[1,0,1]
	v_lshlrev_b32_e32 v56, 16, v220
	v_and_b32_e32 v57, 0xffff0000, v220
	v_lshlrev_b32_e32 v58, 16, v221
	v_and_b32_e32 v59, 0xffff0000, v221
	v_pk_fma_f32 v[50:51], v[50:51], 0.5, v[58:59] op_sel_hi:[1,0,1]
	v_pk_fma_f32 v[48:49], v[48:49], 0.5, v[56:57] op_sel_hi:[1,0,1]
	global_store_dwordx4 v[96:97], v[48:51], off offset:512
	global_store_dwordx4 v[96:97], v[52:55], off offset:528
	s_nop 0
	v_lshlrev_b32_e32 v50, 16, v226
	v_and_b32_e32 v51, 0xffff0000, v226
	v_lshlrev_b32_e32 v52, 16, v227
	v_and_b32_e32 v53, 0xffff0000, v227
	v_pk_fma_f32 v[46:47], v[46:47], 0.5, v[52:53] op_sel_hi:[1,0,1]
	v_pk_fma_f32 v[44:45], v[44:45], 0.5, v[50:51] op_sel_hi:[1,0,1]
	v_lshlrev_b32_e32 v50, 16, v224
	v_and_b32_e32 v51, 0xffff0000, v224
	v_lshlrev_b32_e32 v52, 16, v225
	v_and_b32_e32 v53, 0xffff0000, v225
	v_lshl_add_u64 v[48:49], v[98:99], 2, s[50:51]
	v_pk_fma_f32 v[42:43], v[42:43], 0.5, v[52:53] op_sel_hi:[1,0,1]
	v_pk_fma_f32 v[40:41], v[40:41], 0.5, v[50:51] op_sel_hi:[1,0,1]
	global_store_dwordx4 v[48:49], v[40:43], off
	global_store_dwordx4 v[48:49], v[44:47], off offset:16
	s_nop 0
	v_lshlrev_b32_e32 v40, 16, v230
	v_and_b32_e32 v41, 0xffff0000, v230
	v_lshlrev_b32_e32 v42, 16, v231
	v_and_b32_e32 v43, 0xffff0000, v231
	v_pk_fma_f32 v[38:39], v[38:39], 0.5, v[42:43] op_sel_hi:[1,0,1]
	v_pk_fma_f32 v[36:37], v[36:37], 0.5, v[40:41] op_sel_hi:[1,0,1]
	v_lshlrev_b32_e32 v40, 16, v228
	v_and_b32_e32 v41, 0xffff0000, v228
	v_lshlrev_b32_e32 v42, 16, v229
	v_and_b32_e32 v43, 0xffff0000, v229
	v_pk_fma_f32 v[34:35], v[34:35], 0.5, v[42:43] op_sel_hi:[1,0,1]
	v_pk_fma_f32 v[32:33], v[32:33], 0.5, v[40:41] op_sel_hi:[1,0,1]
	global_store_dwordx4 v[48:49], v[32:35], off offset:512
	global_store_dwordx4 v[48:49], v[36:39], off offset:528
	s_nop 0
	v_lshlrev_b32_e32 v34, 16, v234
	v_and_b32_e32 v35, 0xffff0000, v234
	v_lshlrev_b32_e32 v36, 16, v235
	v_and_b32_e32 v37, 0xffff0000, v235
	v_pk_fma_f32 v[30:31], v[30:31], 0.5, v[36:37] op_sel_hi:[1,0,1]
	v_pk_fma_f32 v[28:29], v[28:29], 0.5, v[34:35] op_sel_hi:[1,0,1]
	v_lshlrev_b32_e32 v34, 16, v232
	v_and_b32_e32 v35, 0xffff0000, v232
	v_lshlrev_b32_e32 v36, 16, v233
	v_and_b32_e32 v37, 0xffff0000, v233
	v_lshl_add_u64 v[32:33], v[100:101], 2, s[50:51]
	v_pk_fma_f32 v[26:27], v[26:27], 0.5, v[36:37] op_sel_hi:[1,0,1]
	v_pk_fma_f32 v[24:25], v[24:25], 0.5, v[34:35] op_sel_hi:[1,0,1]
	global_store_dwordx4 v[32:33], v[24:27], off
	global_store_dwordx4 v[32:33], v[28:31], off offset:16
	s_nop 0
	v_lshlrev_b32_e32 v24, 16, v238
	v_and_b32_e32 v25, 0xffff0000, v238
	v_lshlrev_b32_e32 v26, 16, v239
	v_and_b32_e32 v27, 0xffff0000, v239
	v_pk_fma_f32 v[22:23], v[22:23], 0.5, v[26:27] op_sel_hi:[1,0,1]
	v_pk_fma_f32 v[20:21], v[20:21], 0.5, v[24:25] op_sel_hi:[1,0,1]
	v_lshlrev_b32_e32 v24, 16, v236
	v_and_b32_e32 v25, 0xffff0000, v236
	v_lshlrev_b32_e32 v26, 16, v237
	v_and_b32_e32 v27, 0xffff0000, v237
	v_pk_fma_f32 v[18:19], v[18:19], 0.5, v[26:27] op_sel_hi:[1,0,1]
	v_pk_fma_f32 v[16:17], v[16:17], 0.5, v[24:25] op_sel_hi:[1,0,1]
	global_store_dwordx4 v[32:33], v[16:19], off offset:512
	global_store_dwordx4 v[32:33], v[20:23], off offset:528
	s_nop 0
	v_lshlrev_b32_e32 v18, 16, v246
	v_and_b32_e32 v19, 0xffff0000, v246
	v_lshlrev_b32_e32 v20, 16, v247
	v_and_b32_e32 v21, 0xffff0000, v247
	v_pk_fma_f32 v[14:15], v[14:15], 0.5, v[20:21] op_sel_hi:[1,0,1]
	v_pk_fma_f32 v[12:13], v[12:13], 0.5, v[18:19] op_sel_hi:[1,0,1]
	v_lshlrev_b32_e32 v18, 16, v244
	v_and_b32_e32 v19, 0xffff0000, v244
	v_lshlrev_b32_e32 v20, 16, v245
	v_and_b32_e32 v21, 0xffff0000, v245
	v_lshl_add_u64 v[16:17], v[102:103], 2, s[50:51]
	v_pk_fma_f32 v[10:11], v[10:11], 0.5, v[20:21] op_sel_hi:[1,0,1]
	v_pk_fma_f32 v[8:9], v[8:9], 0.5, v[18:19] op_sel_hi:[1,0,1]
	global_store_dwordx4 v[16:17], v[8:11], off
	global_store_dwordx4 v[16:17], v[12:15], off offset:16
	s_nop 0
	v_lshlrev_b32_e32 v8, 16, v242
	v_and_b32_e32 v9, 0xffff0000, v242
	v_lshlrev_b32_e32 v10, 16, v243
	v_and_b32_e32 v11, 0xffff0000, v243
	v_pk_fma_f32 v[6:7], v[6:7], 0.5, v[10:11] op_sel_hi:[1,0,1]
	v_pk_fma_f32 v[4:5], v[4:5], 0.5, v[8:9] op_sel_hi:[1,0,1]
	v_lshlrev_b32_e32 v8, 16, v240
	v_and_b32_e32 v9, 0xffff0000, v240
	v_lshlrev_b32_e32 v10, 16, v241
	v_and_b32_e32 v11, 0xffff0000, v241
	v_pk_fma_f32 v[2:3], v[2:3], 0.5, v[10:11] op_sel_hi:[1,0,1]
	v_pk_fma_f32 v[0:1], v[0:1], 0.5, v[8:9] op_sel_hi:[1,0,1]
	global_store_dwordx4 v[16:17], v[0:3], off offset:512
	global_store_dwordx4 v[16:17], v[4:7], off offset:528
